# P3 EpiProj path 3: 296 compiler-packed v_pk_{mul,add,fma}_f32 replaced by scalar f32 pairs (same rounding)
# speedup vs baseline: 1.0036x; 1.0036x over previous
; __device__ __forceinline__ unsigned pk2(float lo, float hi) { return pg8::cvt_pk_bf16(lo, hi); }
;     __device__ __forceinline__ void operator()(const f32x4 (&acc)[2][2][4][2], const pg8::Unit& u, int wr, int wc, int fr, int fq) const {
;     ...
;             const float* w = (u.pn < 2) ? qw : kw; const float sc = (u.pn < 2) ? 0.125f * LOG2E : 1.f;
;             f32x4 wv[2][2];
; #pragma unroll
;             for (int bj = 0; bj < 2; ++bj)
; #pragma unroll
;                 for (int n = 0; n < 2; ++n) wv[bj][n] = *(const f32x4*)(w + 32 * bj + 8 * fq + 4 * n);
; #pragma unroll
;             for (int ai = 0; ai < 2; ++ai)
; #pragma unroll
;                 for (int m = 0; m < 4; ++m) {
;                     const int row = row0 + ai * 128 + m * 16;
;                     const float rs = rsqrtf(sumsq[row] * (1.f / 1024.f) + EPS);
;                     f32x4 v[2][2]; float ss = 0.f;
; #pragma unroll
;                     for (int bj = 0; bj < 2; ++bj)
; #pragma unroll
;                         for (int n = 0; n < 2; ++n) { v[bj][n] = acc[ai][bj][m][n] * rs; ss += (v[bj][n][0] * v[bj][n][0] + v[bj][n][1] * v[bj][n][1]) + (v[bj][n][2] * v[bj][n][2] + v[bj][n][3] * v[bj][n][3]); }
;                     ss += __shfl_xor(ss, 16); ss += __shfl_xor(ss, 32);
;                     const float r = rsqrtf(ss * (1.f / 64.f) + EPS) * sc;
; #pragma unroll
;                     for (int bj = 0; bj < 2; ++bj) {
;                         const f32x4 a = v[bj][0] * wv[bj][0] * r, b = v[bj][1] * wv[bj][1] * r;
;                         u32x4 o; o.x = pk2(a[0], a[1]); o.y = pk2(a[2], a[3]); o.z = pk2(b[0], b[1]); o.w = pk2(b[2], b[3]);
.LBB0_387:
	v_readlane_b32 s0, v235, 2
	v_ashrrev_i32_e32 v165, 31, v164
	v_readlane_b32 s2, v235, 4
	v_readlane_b32 s3, v235, 5
	s_cmp_lt_i32 s57, 2
	v_readlane_b32 s1, v235, 3
	v_lshl_add_u64 v[166:167], v[164:165], 2, s[2:3]
	global_load_dword v179, v[166:167], off
	global_load_dword v236, v[166:167], off offset:64
	global_load_dword v237, v[166:167], off offset:128
	global_load_dword v238, v[166:167], off offset:192
	global_load_dword v239, v[166:167], off offset:512
	global_load_dword v240, v[166:167], off offset:576
	global_load_dword v241, v[166:167], off offset:640
	global_load_dword v242, v[166:167], off offset:704
	s_cselect_b64 vcc, -1, 0
	v_readlane_b32 s60, v235, 14
	s_and_b64 s[0:1], vcc, exec
	v_readlane_b32 s61, v235, 15
	v_lshlrev_b32_e32 v128, 2, v154
	s_cselect_b32 s1, s27, s61
	s_cselect_b32 s0, s26, s60
	global_load_dwordx4 v[140:143], v128, s[0:1]
	global_load_dwordx4 v[136:139], v128, s[0:1] offset:16
	global_load_dwordx4 v[132:135], v128, s[0:1] offset:128
	s_nop 0
	global_load_dwordx4 v[128:131], v128, s[0:1] offset:144
	v_and_b32_e32 v178, 64, v176
	v_xor_b32_e32 v177, 16, v176
	v_add_u32_e32 v178, 64, v178
	v_cndmask_b32_e32 v165, 1.0, v175, vcc
	v_xor_b32_e32 v182, 32, v176
	v_cmp_lt_i32_e32 vcc, v177, v178
	v_readlane_b32 s0, v235, 33
	v_readlane_b32 s1, v235, 34
	v_cndmask_b32_e32 v177, v176, v177, vcc
	v_cmp_lt_i32_e32 vcc, v182, v178
	v_lshlrev_b32_e32 v178, 2, v177
	v_mov_b64_e32 v[168:169], s[0:1]
	v_cndmask_b32_e32 v182, v176, v182, vcc
	v_lshlrev_b32_e32 v177, 2, v182
	v_mad_i64_i32 v[180:181], s[0:1], v164, s55, v[168:169]
	s_lshl_b32 s0, s57, 8
	s_ashr_i32 s1, s0, 31
	s_lshl_b64 s[0:1], s[0:1], 1
	v_lshl_add_u64 v[180:181], v[180:181], 0, s[0:1]
	v_lshlrev_b32_e32 v152, 1, v154
	v_lshl_add_u64 v[180:181], v[180:181], 0, s[12:13]
	v_lshl_add_u64 v[180:181], v[180:181], 0, v[152:153]
	v_readlane_b32 s62, v235, 16
	v_readlane_b32 s63, v235, 17
	v_readlane_b32 s64, v235, 18
	v_readlane_b32 s65, v235, 19
	v_readlane_b32 s66, v235, 20
	v_readlane_b32 s67, v235, 21
	v_readlane_b32 s68, v235, 22
	v_readlane_b32 s69, v235, 23
	v_readlane_b32 s70, v235, 24
	v_readlane_b32 s71, v235, 25
	v_readlane_b32 s72, v235, 26
	v_readlane_b32 s73, v235, 27
	v_readlane_b32 s74, v235, 28
	v_readlane_b32 s75, v235, 29
	s_waitcnt vmcnt(0)
	v_fmamk_f32 v179, v179, 0x3a800000, v174
	v_mul_f32_e32 v182, 0x4b800000, v179
	v_cmp_gt_f32_e32 vcc, s54, v179
	s_nop 1
	v_cndmask_b32_e32 v179, v179, v182, vcc
	v_rsq_f32_e32 v179, v179
	s_nop 0
	v_mul_f32_e32 v182, 0x45800000, v179
	v_cndmask_b32_e32 v182, v179, v182, vcc
	v_mul_f32_e32 v124, v124, v182
	v_mul_f32_e32 v125, v125, v182
	v_mul_f32_e32 v126, v126, v182
	v_mul_f32_e32 v127, v127, v182
	v_mul_f32_e32 v120, v120, v182
	v_mul_f32_e32 v121, v121, v182
	v_mul_f32_e32 v122, v122, v182
	v_mul_f32_e32 v123, v123, v182
	v_mul_f32_e32 v118, v118, v182
	v_mul_f32_e32 v119, v119, v182
	v_mul_f32_e32 v116, v116, v182
	v_mul_f32_e32 v117, v117, v182
	v_mul_f32_e32 v114, v114, v182
	v_mul_f32_e32 v115, v115, v182
	v_mul_f32_e32 v112, v112, v182
	v_mul_f32_e32 v113, v113, v182
	v_mul_f32_e32 v182, v126, v126
	v_mul_f32_e32 v183, v127, v127
	v_mul_f32_e32 v184, v124, v124
	v_mul_f32_e32 v185, v125, v125
	v_mul_f32_e32 v186, v122, v122
	v_mul_f32_e32 v187, v123, v123
	v_mul_f32_e32 v192, v120, v120
	v_mul_f32_e32 v193, v121, v121
	v_pk_mov_b32 v[196:197], v[184:185], v[182:183] op_sel:[1,0]
	v_mov_b32_e32 v185, v183
	v_pk_mov_b32 v[182:183], v[192:193], v[186:187] op_sel:[1,0]
	v_mov_b32_e32 v193, v187
	v_mul_f32_e32 v188, v116, v116
	v_mul_f32_e32 v194, v118, v118
	v_add_f32_e32 v184, v196, v184
	v_add_f32_e32 v185, v197, v185
	v_add_f32_e32 v182, v182, v192
	v_add_f32_e32 v183, v183, v193
	v_fma_f32 v186, v116, v116, v188
	v_fma_f32 v187, v117, v117, v188
	v_fma_f32 v195, v119, v119, v194
	v_fma_f32 v194, v118, v118, v194
	v_add_f32_e32 v185, v184, v185
	v_add_f32_e32 v184, v184, v184
	v_add_f32_e32 v183, v182, v183
	v_add_f32_e32 v182, v182, v182
	v_mul_f32_e32 v186, v112, v112
	v_mul_f32_e32 v194, v113, v113
	v_mul_f32_e32 v184, v114, v114
	v_mul_f32_e32 v182, v115, v115
	v_add_f32_e32 v186, v186, v194
	v_add_f32_e32 v187, v187, v195
	v_add_f32_e32 v182, v184, v182
	v_add_f32_e32 v183, v185, v183
	v_mul_f32_e32 v124, v140, v124
	v_mul_f32_e32 v125, v141, v125
	v_add_f32_e32 v182, v186, v182
	v_add_f32_e32 v183, v187, v183
	v_mul_f32_e32 v126, v142, v126
	v_mul_f32_e32 v127, v143, v127
	v_add_f32_e32 v179, v182, v183
	ds_bpermute_b32 v182, v178, v179
	v_mul_f32_e32 v120, v136, v120
	v_mul_f32_e32 v121, v137, v121
	v_mul_f32_e32 v122, v138, v122
	v_mul_f32_e32 v123, v139, v123
	v_mul_f32_e32 v116, v132, v116
	v_mul_f32_e32 v117, v133, v117
	v_mul_f32_e32 v118, v134, v118
	v_mul_f32_e32 v119, v135, v119
	s_waitcnt lgkmcnt(0)
	v_add_f32_e32 v179, v179, v182
	ds_bpermute_b32 v182, v177, v179
	v_mul_f32_e32 v112, v128, v112
	v_mul_f32_e32 v113, v129, v113
	v_mul_f32_e32 v114, v130, v114
	v_mul_f32_e32 v115, v131, v115
	s_waitcnt lgkmcnt(0)
; __device__ __forceinline__ unsigned pk2(float lo, float hi) { return pg8::cvt_pk_bf16(lo, hi); }
;     __device__ __forceinline__ void operator()(const f32x4 (&acc)[2][2][4][2], const pg8::Unit& u, int wr, int wc, int fr, int fq) const {
;     ...
;                 for (int m = 0; m < 4; ++m) {
;                     const int row = row0 + ai * 128 + m * 16;
;                     const float rs = rsqrtf(sumsq[row] * (1.f / 1024.f) + EPS);
;                     f32x4 v[2][2]; float ss = 0.f;
; #pragma unroll
;                     for (int bj = 0; bj < 2; ++bj)
; #pragma unroll
;                         for (int n = 0; n < 2; ++n) { v[bj][n] = acc[ai][bj][m][n] * rs; ss += (v[bj][n][0] * v[bj][n][0] + v[bj][n][1] * v[bj][n][1]) + (v[bj][n][2] * v[bj][n][2] + v[bj][n][3] * v[bj][n][3]); }
;                     ss += __shfl_xor(ss, 16); ss += __shfl_xor(ss, 32);
;                     const float r = rsqrtf(ss * (1.f / 64.f) + EPS) * sc;
; #pragma unroll
;                     for (int bj = 0; bj < 2; ++bj) {
;                         const f32x4 a = v[bj][0] * wv[bj][0] * r, b = v[bj][1] * wv[bj][1] * r;
;                         u32x4 o; o.x = pk2(a[0], a[1]); o.y = pk2(a[2], a[3]); o.z = pk2(b[0], b[1]); o.w = pk2(b[2], b[3]);
;                         *(u32x4*)(P + (size_t)row * PW + u.pn * 256 + 64 * wc + 32 * bj + 8 * fq) = o;
;                     }
	v_add_f32_e32 v179, v179, v182
	v_fmamk_f32 v179, v179, 0x3c800000, v174
	v_mul_f32_e32 v182, 0x4b800000, v179
	v_cmp_gt_f32_e32 vcc, s54, v179
	s_nop 1
	v_cndmask_b32_e32 v179, v179, v182, vcc
	v_rsq_f32_e32 v179, v179
	s_nop 0
	v_mul_f32_e32 v182, 0x45800000, v179
	v_cndmask_b32_e32 v179, v179, v182, vcc
	v_mul_f32_e32 v182, v165, v179
	v_mul_f32_e32 v126, v126, v182
	v_mul_f32_e32 v127, v127, v182
	v_mul_f32_e32 v124, v124, v182
	v_mul_f32_e32 v125, v125, v182
	v_mul_f32_e32 v122, v122, v182
	v_mul_f32_e32 v123, v123, v182
	v_mul_f32_e32 v120, v120, v182
	v_mul_f32_e32 v121, v121, v182
	v_mul_f32_e32 v118, v118, v182
	v_mul_f32_e32 v119, v119, v182
	v_mul_f32_e32 v116, v116, v182
	v_mul_f32_e32 v117, v117, v182
	v_mul_f32_e32 v184, v114, v182
	v_mul_f32_e32 v185, v115, v182
	v_mul_f32_e32 v183, v113, v182
	v_mul_f32_e32 v182, v112, v182
	v_cvt_pk_bf16_f32 v112, v124, v125
	v_cvt_pk_bf16_f32 v113, v126, v127
	v_cvt_pk_bf16_f32 v114, v120, v121
	v_cvt_pk_bf16_f32 v115, v122, v123
	global_store_dwordx4 v[180:181], v[112:115], off
	s_nop 1
	v_cvt_pk_bf16_f32 v112, v116, v117
	v_cvt_pk_bf16_f32 v113, v118, v119
	v_cvt_pk_bf16_f32 v114, v182, v183
	v_cvt_pk_bf16_f32 v115, v184, v185
	global_store_dwordx4 v[180:181], v[112:115], off offset:64
	s_nop 0
	s_nop 0
	v_fmamk_f32 v112, v236, 0x3a800000, v174
	v_mul_f32_e32 v113, 0x4b800000, v112
	v_cmp_gt_f32_e32 vcc, s54, v112
	s_nop 1
	v_cndmask_b32_e32 v112, v112, v113, vcc
	v_rsq_f32_e32 v114, v112
	v_or_b32_e32 v112, 16, v164
	v_mad_i64_i32 v[112:113], s[2:3], v112, s55, v[168:169]
	v_mul_f32_e32 v115, 0x45800000, v114
	v_cndmask_b32_e32 v114, v114, v115, vcc
	v_mul_f32_e32 v108, v108, v114
	v_mul_f32_e32 v109, v109, v114
	v_mul_f32_e32 v110, v110, v114
	v_mul_f32_e32 v111, v111, v114
	v_mul_f32_e32 v104, v104, v114
	v_mul_f32_e32 v105, v105, v114
	v_mul_f32_e32 v106, v106, v114
	v_mul_f32_e32 v107, v107, v114
	v_mul_f32_e32 v102, v102, v114
	v_mul_f32_e32 v103, v103, v114
	v_mul_f32_e32 v100, v100, v114
	v_mul_f32_e32 v101, v101, v114
	v_mul_f32_e32 v98, v98, v114
	v_mul_f32_e32 v99, v99, v114
	v_mul_f32_e32 v96, v96, v114
	v_mul_f32_e32 v97, v97, v114
	v_mul_f32_e32 v114, v110, v110
	v_mul_f32_e32 v115, v111, v111
	v_mul_f32_e32 v116, v108, v108
	v_mul_f32_e32 v117, v109, v109
	v_mul_f32_e32 v118, v106, v106
	v_mul_f32_e32 v119, v107, v107
	v_mul_f32_e32 v120, v104, v104
	v_mul_f32_e32 v121, v105, v105
	v_pk_mov_b32 v[126:127], v[116:117], v[114:115] op_sel:[1,0]
	v_mov_b32_e32 v117, v115
	v_pk_mov_b32 v[114:115], v[120:121], v[118:119] op_sel:[1,0]
	v_mov_b32_e32 v121, v119
	v_mul_f32_e32 v122, v100, v100
	v_mul_f32_e32 v124, v102, v102
	v_add_f32_e32 v116, v126, v116
	v_add_f32_e32 v117, v127, v117
	v_add_f32_e32 v114, v114, v120
	v_add_f32_e32 v115, v115, v121
	v_fma_f32 v118, v100, v100, v122
	v_fma_f32 v119, v101, v101, v122
	v_fma_f32 v122, v102, v102, v124
	v_fma_f32 v123, v103, v103, v124
	v_add_f32_e32 v117, v116, v117
	v_add_f32_e32 v116, v116, v116
	v_add_f32_e32 v115, v114, v115
	v_add_f32_e32 v114, v114, v114
	v_mul_f32_e32 v118, v96, v96
	v_mul_f32_e32 v122, v97, v97
	v_mul_f32_e32 v116, v98, v98
	v_mul_f32_e32 v114, v99, v99
	v_add_f32_e32 v118, v118, v122
	v_add_f32_e32 v119, v119, v123
	v_add_f32_e32 v114, v116, v114
	v_add_f32_e32 v115, v117, v115
	v_lshl_add_u64 v[112:113], v[112:113], 0, s[0:1]
	v_add_f32_e32 v114, v118, v114
	v_add_f32_e32 v115, v119, v115
	v_lshl_add_u64 v[112:113], v[112:113], 0, s[12:13]
	v_add_f32_e32 v114, v114, v115
	ds_bpermute_b32 v115, v178, v114
	v_mul_f32_e32 v108, v140, v108
	v_mul_f32_e32 v109, v141, v109
	v_mul_f32_e32 v110, v142, v110
	v_mul_f32_e32 v111, v143, v111
	v_mul_f32_e32 v104, v136, v104
	v_mul_f32_e32 v105, v137, v105
	v_mul_f32_e32 v106, v138, v106
	v_mul_f32_e32 v107, v139, v107
	s_waitcnt lgkmcnt(0)
	v_add_f32_e32 v114, v114, v115
	ds_bpermute_b32 v115, v177, v114
	v_mul_f32_e32 v100, v132, v100
	v_mul_f32_e32 v101, v133, v101
	v_mul_f32_e32 v102, v134, v102
	v_mul_f32_e32 v103, v135, v103
	v_mul_f32_e32 v96, v128, v96
	v_mul_f32_e32 v97, v129, v97
	v_mul_f32_e32 v98, v130, v98
	v_mul_f32_e32 v99, v131, v99
	s_waitcnt lgkmcnt(0)
	v_add_f32_e32 v114, v114, v115
	v_fmamk_f32 v114, v114, 0x3c800000, v174
	v_mul_f32_e32 v115, 0x4b800000, v114
	v_cmp_gt_f32_e32 vcc, s54, v114
	v_lshl_add_u64 v[112:113], v[112:113], 0, v[152:153]
	s_nop 0
	v_cndmask_b32_e32 v114, v114, v115, vcc
	v_rsq_f32_e32 v114, v114
	s_nop 0
	v_mul_f32_e32 v115, 0x45800000, v114
	v_cndmask_b32_e32 v114, v114, v115, vcc
	v_mul_f32_e32 v114, v165, v114
	v_mul_f32_e32 v110, v110, v114
	v_mul_f32_e32 v111, v111, v114
	v_mul_f32_e32 v108, v108, v114
	v_mul_f32_e32 v109, v109, v114
	v_mul_f32_e32 v106, v106, v114
	v_mul_f32_e32 v107, v107, v114
	v_mul_f32_e32 v104, v104, v114
	v_mul_f32_e32 v105, v105, v114
	v_mul_f32_e32 v102, v102, v114
	v_mul_f32_e32 v103, v103, v114
	v_mul_f32_e32 v100, v100, v114
	v_mul_f32_e32 v101, v101, v114
	v_mul_f32_e32 v116, v98, v114
	v_mul_f32_e32 v117, v99, v114
	v_mul_f32_e32 v115, v97, v114
	v_mul_f32_e32 v114, v96, v114
	v_cvt_pk_bf16_f32 v96, v108, v109
	v_cvt_pk_bf16_f32 v97, v110, v111
	v_cvt_pk_bf16_f32 v98, v104, v105
	v_cvt_pk_bf16_f32 v99, v106, v107
	global_store_dwordx4 v[112:113], v[96:99], off
	s_nop 1
	v_cvt_pk_bf16_f32 v96, v100, v101
	v_cvt_pk_bf16_f32 v97, v102, v103
	v_cvt_pk_bf16_f32 v98, v114, v115
	v_cvt_pk_bf16_f32 v99, v116, v117
	global_store_dwordx4 v[112:113], v[96:99], off offset:64
	s_nop 0
	s_nop 0
	v_fmamk_f32 v96, v237, 0x3a800000, v174
	v_mul_f32_e32 v97, 0x4b800000, v96
	v_cmp_gt_f32_e32 vcc, s54, v96
	s_nop 1
	v_cndmask_b32_e32 v96, v96, v97, vcc
	v_rsq_f32_e32 v98, v96
	v_or_b32_e32 v96, 32, v164
; __device__ __forceinline__ unsigned pk2(float lo, float hi) { return pg8::cvt_pk_bf16(lo, hi); }
;     __device__ __forceinline__ void operator()(const f32x4 (&acc)[2][2][4][2], const pg8::Unit& u, int wr, int wc, int fr, int fq) const {
;     ...
;                 for (int m = 0; m < 4; ++m) {
;                     const int row = row0 + ai * 128 + m * 16;
;                     const float rs = rsqrtf(sumsq[row] * (1.f / 1024.f) + EPS);
;                     f32x4 v[2][2]; float ss = 0.f;
; #pragma unroll
;                     for (int bj = 0; bj < 2; ++bj)
; #pragma unroll
;                         for (int n = 0; n < 2; ++n) { v[bj][n] = acc[ai][bj][m][n] * rs; ss += (v[bj][n][0] * v[bj][n][0] + v[bj][n][1] * v[bj][n][1]) + (v[bj][n][2] * v[bj][n][2] + v[bj][n][3] * v[bj][n][3]); }
;                     ss += __shfl_xor(ss, 16); ss += __shfl_xor(ss, 32);
;                     const float r = rsqrtf(ss * (1.f / 64.f) + EPS) * sc;
; #pragma unroll
;                     for (int bj = 0; bj < 2; ++bj) {
;                         const f32x4 a = v[bj][0] * wv[bj][0] * r, b = v[bj][1] * wv[bj][1] * r;
;                         u32x4 o; o.x = pk2(a[0], a[1]); o.y = pk2(a[2], a[3]); o.z = pk2(b[0], b[1]); o.w = pk2(b[2], b[3]);
;                         *(u32x4*)(P + (size_t)row * PW + u.pn * 256 + 64 * wc + 32 * bj + 8 * fq) = o;
;                     }
	v_mad_i64_i32 v[96:97], s[2:3], v96, s55, v[168:169]
	v_mul_f32_e32 v99, 0x45800000, v98
	v_cndmask_b32_e32 v98, v98, v99, vcc
	v_mul_f32_e32 v92, v92, v98
	v_mul_f32_e32 v93, v93, v98
	v_mul_f32_e32 v94, v94, v98
	v_mul_f32_e32 v95, v95, v98
	v_mul_f32_e32 v88, v88, v98
	v_mul_f32_e32 v89, v89, v98
	v_mul_f32_e32 v90, v90, v98
	v_mul_f32_e32 v91, v91, v98
	v_mul_f32_e32 v86, v86, v98
	v_mul_f32_e32 v87, v87, v98
	v_mul_f32_e32 v84, v84, v98
	v_mul_f32_e32 v85, v85, v98
	v_mul_f32_e32 v82, v82, v98
	v_mul_f32_e32 v83, v83, v98
	v_mul_f32_e32 v80, v80, v98
	v_mul_f32_e32 v81, v81, v98
	v_mul_f32_e32 v98, v94, v94
	v_mul_f32_e32 v99, v95, v95
	v_mul_f32_e32 v100, v92, v92
	v_mul_f32_e32 v101, v93, v93
	v_mul_f32_e32 v102, v90, v90
	v_mul_f32_e32 v103, v91, v91
	v_mul_f32_e32 v104, v88, v88
	v_mul_f32_e32 v105, v89, v89
	v_pk_mov_b32 v[110:111], v[100:101], v[98:99] op_sel:[1,0]
	v_mov_b32_e32 v101, v99
	v_pk_mov_b32 v[98:99], v[104:105], v[102:103] op_sel:[1,0]
	v_mov_b32_e32 v105, v103
	v_mul_f32_e32 v106, v84, v84
	v_mul_f32_e32 v108, v86, v86
	v_add_f32_e32 v100, v110, v100
	v_add_f32_e32 v101, v111, v101
	v_add_f32_e32 v98, v98, v104
	v_add_f32_e32 v99, v99, v105
	v_fma_f32 v102, v84, v84, v106
	v_fma_f32 v103, v85, v85, v106
	v_fma_f32 v106, v86, v86, v108
	v_fma_f32 v107, v87, v87, v108
	v_add_f32_e32 v101, v100, v101
	v_add_f32_e32 v100, v100, v100
	v_add_f32_e32 v99, v98, v99
	v_add_f32_e32 v98, v98, v98
	v_mul_f32_e32 v102, v80, v80
	v_mul_f32_e32 v106, v81, v81
	v_mul_f32_e32 v100, v82, v82
	v_mul_f32_e32 v98, v83, v83
	v_add_f32_e32 v102, v102, v106
	v_add_f32_e32 v103, v103, v107
	v_add_f32_e32 v98, v100, v98
	v_add_f32_e32 v99, v101, v99
	v_lshl_add_u64 v[96:97], v[96:97], 0, s[0:1]
	v_add_f32_e32 v98, v102, v98
	v_add_f32_e32 v99, v103, v99
	v_lshl_add_u64 v[96:97], v[96:97], 0, s[12:13]
	v_add_f32_e32 v98, v98, v99
	ds_bpermute_b32 v99, v178, v98
	v_mul_f32_e32 v92, v140, v92
	v_mul_f32_e32 v93, v141, v93
	v_mul_f32_e32 v94, v142, v94
	v_mul_f32_e32 v95, v143, v95
	v_mul_f32_e32 v88, v136, v88
	v_mul_f32_e32 v89, v137, v89
	v_mul_f32_e32 v90, v138, v90
	v_mul_f32_e32 v91, v139, v91
	s_waitcnt lgkmcnt(0)
	v_add_f32_e32 v98, v98, v99
	ds_bpermute_b32 v99, v177, v98
	v_mul_f32_e32 v84, v132, v84
	v_mul_f32_e32 v85, v133, v85
	v_mul_f32_e32 v86, v134, v86
	v_mul_f32_e32 v87, v135, v87
	v_mul_f32_e32 v80, v128, v80
	v_mul_f32_e32 v81, v129, v81
	v_mul_f32_e32 v82, v130, v82
	v_mul_f32_e32 v83, v131, v83
	s_waitcnt lgkmcnt(0)
	v_add_f32_e32 v98, v98, v99
	v_fmamk_f32 v98, v98, 0x3c800000, v174
	v_mul_f32_e32 v99, 0x4b800000, v98
	v_cmp_gt_f32_e32 vcc, s54, v98
	v_lshl_add_u64 v[96:97], v[96:97], 0, v[152:153]
	s_nop 0
	v_cndmask_b32_e32 v98, v98, v99, vcc
	v_rsq_f32_e32 v98, v98
	s_nop 0
	v_mul_f32_e32 v99, 0x45800000, v98
	v_cndmask_b32_e32 v98, v98, v99, vcc
	v_mul_f32_e32 v98, v165, v98
	v_mul_f32_e32 v94, v94, v98
	v_mul_f32_e32 v95, v95, v98
	v_mul_f32_e32 v92, v92, v98
	v_mul_f32_e32 v93, v93, v98
	v_mul_f32_e32 v90, v90, v98
	v_mul_f32_e32 v91, v91, v98
	v_mul_f32_e32 v88, v88, v98
	v_mul_f32_e32 v89, v89, v98
	v_mul_f32_e32 v86, v86, v98
	v_mul_f32_e32 v87, v87, v98
	v_mul_f32_e32 v84, v84, v98
	v_mul_f32_e32 v85, v85, v98
	v_mul_f32_e32 v100, v82, v98
	v_mul_f32_e32 v101, v83, v98
	v_mul_f32_e32 v99, v81, v98
	v_mul_f32_e32 v98, v80, v98
	v_cvt_pk_bf16_f32 v80, v92, v93
	v_cvt_pk_bf16_f32 v81, v94, v95
	v_cvt_pk_bf16_f32 v82, v88, v89
	v_cvt_pk_bf16_f32 v83, v90, v91
	global_store_dwordx4 v[96:97], v[80:83], off
	s_nop 1
	v_cvt_pk_bf16_f32 v80, v84, v85
	v_cvt_pk_bf16_f32 v81, v86, v87
	v_cvt_pk_bf16_f32 v82, v98, v99
	v_cvt_pk_bf16_f32 v83, v100, v101
	global_store_dwordx4 v[96:97], v[80:83], off offset:64
	s_nop 0
	s_nop 0
	v_fmamk_f32 v80, v238, 0x3a800000, v174
	v_mul_f32_e32 v81, 0x4b800000, v80
	v_cmp_gt_f32_e32 vcc, s54, v80
	s_nop 1
	v_cndmask_b32_e32 v80, v80, v81, vcc
	v_rsq_f32_e32 v82, v80
	v_or_b32_e32 v80, 48, v164
	v_mad_i64_i32 v[80:81], s[2:3], v80, s55, v[168:169]
	v_mul_f32_e32 v83, 0x45800000, v82
	v_cndmask_b32_e32 v82, v82, v83, vcc
	v_mul_f32_e32 v76, v76, v82
	v_mul_f32_e32 v77, v77, v82
	v_mul_f32_e32 v78, v78, v82
	v_mul_f32_e32 v79, v79, v82
	v_mul_f32_e32 v72, v72, v82
	v_mul_f32_e32 v73, v73, v82
	v_mul_f32_e32 v74, v74, v82
	v_mul_f32_e32 v75, v75, v82
	v_mul_f32_e32 v70, v70, v82
	v_mul_f32_e32 v71, v71, v82
	v_mul_f32_e32 v68, v68, v82
	v_mul_f32_e32 v69, v69, v82
	v_mul_f32_e32 v66, v66, v82
	v_mul_f32_e32 v67, v67, v82
	v_mul_f32_e32 v64, v64, v82
	v_mul_f32_e32 v65, v65, v82
	v_mul_f32_e32 v82, v78, v78
	v_mul_f32_e32 v83, v79, v79
	v_mul_f32_e32 v84, v76, v76
	v_mul_f32_e32 v85, v77, v77
	v_mul_f32_e32 v86, v74, v74
	v_mul_f32_e32 v87, v75, v75
	v_mul_f32_e32 v88, v72, v72
	v_mul_f32_e32 v89, v73, v73
	v_pk_mov_b32 v[94:95], v[84:85], v[82:83] op_sel:[1,0]
	v_mov_b32_e32 v85, v83
	v_pk_mov_b32 v[82:83], v[88:89], v[86:87] op_sel:[1,0]
	v_mov_b32_e32 v89, v87
	v_mul_f32_e32 v90, v68, v68
	v_mul_f32_e32 v92, v70, v70
	v_add_f32_e32 v84, v94, v84
	v_add_f32_e32 v85, v95, v85
	v_add_f32_e32 v82, v82, v88
	v_add_f32_e32 v83, v83, v89
	v_fma_f32 v86, v68, v68, v90
	v_fma_f32 v87, v69, v69, v90
	v_fma_f32 v90, v70, v70, v92
	v_fma_f32 v91, v71, v71, v92
	v_add_f32_e32 v85, v84, v85
	v_add_f32_e32 v84, v84, v84
	v_add_f32_e32 v83, v82, v83
	v_add_f32_e32 v82, v82, v82
	v_mul_f32_e32 v86, v64, v64
	v_mul_f32_e32 v90, v65, v65
	v_mul_f32_e32 v84, v66, v66
	v_mul_f32_e32 v82, v67, v67
	v_add_f32_e32 v86, v86, v90
	v_add_f32_e32 v87, v87, v91
	v_add_f32_e32 v82, v84, v82
	v_add_f32_e32 v83, v85, v83
	v_lshl_add_u64 v[80:81], v[80:81], 0, s[0:1]
	v_add_f32_e32 v82, v86, v82
	v_add_f32_e32 v83, v87, v83
	v_lshl_add_u64 v[80:81], v[80:81], 0, s[12:13]
	v_add_f32_e32 v82, v82, v83
	ds_bpermute_b32 v83, v178, v82
	v_mul_f32_e32 v76, v140, v76
	v_mul_f32_e32 v77, v141, v77
	v_mul_f32_e32 v78, v142, v78
	v_mul_f32_e32 v79, v143, v79
	v_mul_f32_e32 v72, v136, v72
	v_mul_f32_e32 v73, v137, v73
	v_mul_f32_e32 v74, v138, v74
	v_mul_f32_e32 v75, v139, v75
	s_waitcnt lgkmcnt(0)
; __device__ __forceinline__ unsigned pk2(float lo, float hi) { return pg8::cvt_pk_bf16(lo, hi); }
;     __device__ __forceinline__ void operator()(const f32x4 (&acc)[2][2][4][2], const pg8::Unit& u, int wr, int wc, int fr, int fq) const {
;     ...
;                 for (int m = 0; m < 4; ++m) {
;                     const int row = row0 + ai * 128 + m * 16;
;                     const float rs = rsqrtf(sumsq[row] * (1.f / 1024.f) + EPS);
;                     f32x4 v[2][2]; float ss = 0.f;
; #pragma unroll
;                     for (int bj = 0; bj < 2; ++bj)
; #pragma unroll
;                         for (int n = 0; n < 2; ++n) { v[bj][n] = acc[ai][bj][m][n] * rs; ss += (v[bj][n][0] * v[bj][n][0] + v[bj][n][1] * v[bj][n][1]) + (v[bj][n][2] * v[bj][n][2] + v[bj][n][3] * v[bj][n][3]); }
;                     ss += __shfl_xor(ss, 16); ss += __shfl_xor(ss, 32);
;                     const float r = rsqrtf(ss * (1.f / 64.f) + EPS) * sc;
; #pragma unroll
;                     for (int bj = 0; bj < 2; ++bj) {
;                         const f32x4 a = v[bj][0] * wv[bj][0] * r, b = v[bj][1] * wv[bj][1] * r;
;                         u32x4 o; o.x = pk2(a[0], a[1]); o.y = pk2(a[2], a[3]); o.z = pk2(b[0], b[1]); o.w = pk2(b[2], b[3]);
;                         *(u32x4*)(P + (size_t)row * PW + u.pn * 256 + 64 * wc + 32 * bj + 8 * fq) = o;
;                     }
	v_add_f32_e32 v82, v82, v83
	ds_bpermute_b32 v83, v177, v82
	v_mul_f32_e32 v68, v132, v68
	v_mul_f32_e32 v69, v133, v69
	v_mul_f32_e32 v70, v134, v70
	v_mul_f32_e32 v71, v135, v71
	v_mul_f32_e32 v64, v128, v64
	v_mul_f32_e32 v65, v129, v65
	v_mul_f32_e32 v66, v130, v66
	v_mul_f32_e32 v67, v131, v67
	s_waitcnt lgkmcnt(0)
	v_add_f32_e32 v82, v82, v83
	v_fmamk_f32 v82, v82, 0x3c800000, v174
	v_mul_f32_e32 v83, 0x4b800000, v82
	v_cmp_gt_f32_e32 vcc, s54, v82
	v_lshl_add_u64 v[80:81], v[80:81], 0, v[152:153]
	s_nop 0
	v_cndmask_b32_e32 v82, v82, v83, vcc
	v_rsq_f32_e32 v82, v82
	s_nop 0
	v_mul_f32_e32 v83, 0x45800000, v82
	v_cndmask_b32_e32 v82, v82, v83, vcc
	v_mul_f32_e32 v82, v165, v82
	v_mul_f32_e32 v78, v78, v82
	v_mul_f32_e32 v79, v79, v82
	v_mul_f32_e32 v76, v76, v82
	v_mul_f32_e32 v77, v77, v82
	v_mul_f32_e32 v74, v74, v82
	v_mul_f32_e32 v75, v75, v82
	v_mul_f32_e32 v72, v72, v82
	v_mul_f32_e32 v73, v73, v82
	v_mul_f32_e32 v70, v70, v82
	v_mul_f32_e32 v71, v71, v82
	v_mul_f32_e32 v68, v68, v82
	v_mul_f32_e32 v69, v69, v82
	v_mul_f32_e32 v84, v66, v82
	v_mul_f32_e32 v85, v67, v82
	v_mul_f32_e32 v83, v65, v82
	v_mul_f32_e32 v82, v64, v82
	v_cvt_pk_bf16_f32 v64, v76, v77
	v_cvt_pk_bf16_f32 v65, v78, v79
	v_cvt_pk_bf16_f32 v66, v72, v73
	v_cvt_pk_bf16_f32 v67, v74, v75
	global_store_dwordx4 v[80:81], v[64:67], off
	s_nop 1
	v_cvt_pk_bf16_f32 v64, v68, v69
	v_cvt_pk_bf16_f32 v65, v70, v71
	v_cvt_pk_bf16_f32 v66, v82, v83
	v_cvt_pk_bf16_f32 v67, v84, v85
	global_store_dwordx4 v[80:81], v[64:67], off offset:64
	s_nop 0
	s_nop 0
	v_fmamk_f32 v64, v239, 0x3a800000, v174
	v_mul_f32_e32 v65, 0x4b800000, v64
	v_cmp_gt_f32_e32 vcc, s54, v64
	s_nop 1
	v_cndmask_b32_e32 v64, v64, v65, vcc
	v_rsq_f32_e32 v66, v64
	v_add_u32_e32 v64, 0x80, v164
	v_mad_i64_i32 v[64:65], s[2:3], v64, s55, v[168:169]
	v_mul_f32_e32 v67, 0x45800000, v66
	v_cndmask_b32_e32 v66, v66, v67, vcc
	v_mul_f32_e32 v60, v60, v66
	v_mul_f32_e32 v61, v61, v66
	v_mul_f32_e32 v62, v62, v66
	v_mul_f32_e32 v63, v63, v66
	v_mul_f32_e32 v56, v56, v66
	v_mul_f32_e32 v57, v57, v66
	v_mul_f32_e32 v58, v58, v66
	v_mul_f32_e32 v59, v59, v66
	v_mul_f32_e32 v54, v54, v66
	v_mul_f32_e32 v55, v55, v66
	v_mul_f32_e32 v52, v52, v66
	v_mul_f32_e32 v53, v53, v66
	v_mul_f32_e32 v50, v50, v66
	v_mul_f32_e32 v51, v51, v66
	v_mul_f32_e32 v48, v48, v66
	v_mul_f32_e32 v49, v49, v66
	v_mul_f32_e32 v66, v62, v62
	v_mul_f32_e32 v67, v63, v63
	v_mul_f32_e32 v68, v60, v60
	v_mul_f32_e32 v69, v61, v61
	v_mul_f32_e32 v70, v58, v58
	v_mul_f32_e32 v71, v59, v59
	v_mul_f32_e32 v72, v56, v56
	v_mul_f32_e32 v73, v57, v57
	v_pk_mov_b32 v[78:79], v[68:69], v[66:67] op_sel:[1,0]
	v_mov_b32_e32 v69, v67
	v_pk_mov_b32 v[66:67], v[72:73], v[70:71] op_sel:[1,0]
	v_mov_b32_e32 v73, v71
	v_mul_f32_e32 v74, v52, v52
	v_mul_f32_e32 v76, v54, v54
	v_add_f32_e32 v68, v78, v68
	v_add_f32_e32 v69, v79, v69
	v_add_f32_e32 v66, v66, v72
	v_add_f32_e32 v67, v67, v73
	v_fma_f32 v70, v52, v52, v74
	v_fma_f32 v71, v53, v53, v74
	v_fma_f32 v74, v54, v54, v76
	v_fma_f32 v75, v55, v55, v76
	v_add_f32_e32 v69, v68, v69
	v_add_f32_e32 v68, v68, v68
	v_add_f32_e32 v67, v66, v67
	v_add_f32_e32 v66, v66, v66
	v_mul_f32_e32 v70, v48, v48
	v_mul_f32_e32 v74, v49, v49
	v_mul_f32_e32 v68, v50, v50
	v_mul_f32_e32 v66, v51, v51
	v_add_f32_e32 v70, v70, v74
	v_add_f32_e32 v71, v71, v75
	v_add_f32_e32 v66, v68, v66
	v_add_f32_e32 v67, v69, v67
	v_lshl_add_u64 v[64:65], v[64:65], 0, s[0:1]
	v_add_f32_e32 v66, v70, v66
	v_add_f32_e32 v67, v71, v67
	v_lshl_add_u64 v[64:65], v[64:65], 0, s[12:13]
	v_add_f32_e32 v66, v66, v67
	ds_bpermute_b32 v67, v178, v66
	v_mul_f32_e32 v60, v140, v60
	v_mul_f32_e32 v61, v141, v61
	v_mul_f32_e32 v62, v142, v62
	v_mul_f32_e32 v63, v143, v63
	v_mul_f32_e32 v56, v136, v56
	v_mul_f32_e32 v57, v137, v57
	v_mul_f32_e32 v58, v138, v58
	v_mul_f32_e32 v59, v139, v59
	s_waitcnt lgkmcnt(0)
	v_add_f32_e32 v66, v66, v67
	ds_bpermute_b32 v67, v177, v66
	v_mul_f32_e32 v52, v132, v52
	v_mul_f32_e32 v53, v133, v53
	v_mul_f32_e32 v54, v134, v54
	v_mul_f32_e32 v55, v135, v55
	v_mul_f32_e32 v48, v128, v48
	v_mul_f32_e32 v49, v129, v49
	v_mul_f32_e32 v50, v130, v50
	v_mul_f32_e32 v51, v131, v51
	s_waitcnt lgkmcnt(0)
	v_add_f32_e32 v66, v66, v67
	v_fmamk_f32 v66, v66, 0x3c800000, v174
	v_mul_f32_e32 v67, 0x4b800000, v66
	v_cmp_gt_f32_e32 vcc, s54, v66
	v_lshl_add_u64 v[64:65], v[64:65], 0, v[152:153]
	s_nop 0
	v_cndmask_b32_e32 v66, v66, v67, vcc
	v_rsq_f32_e32 v66, v66
	s_nop 0
	v_mul_f32_e32 v67, 0x45800000, v66
	v_cndmask_b32_e32 v66, v66, v67, vcc
	v_mul_f32_e32 v66, v165, v66
	v_mul_f32_e32 v62, v62, v66
	v_mul_f32_e32 v63, v63, v66
	v_mul_f32_e32 v60, v60, v66
	v_mul_f32_e32 v61, v61, v66
	v_mul_f32_e32 v58, v58, v66
	v_mul_f32_e32 v59, v59, v66
	v_mul_f32_e32 v56, v56, v66
	v_mul_f32_e32 v57, v57, v66
	v_mul_f32_e32 v54, v54, v66
	v_mul_f32_e32 v55, v55, v66
	v_mul_f32_e32 v52, v52, v66
	v_mul_f32_e32 v53, v53, v66
	v_mul_f32_e32 v68, v50, v66
	v_mul_f32_e32 v69, v51, v66
	v_mul_f32_e32 v67, v49, v66
	v_mul_f32_e32 v66, v48, v66
	v_cvt_pk_bf16_f32 v48, v60, v61
	v_cvt_pk_bf16_f32 v49, v62, v63
	v_cvt_pk_bf16_f32 v50, v56, v57
	v_cvt_pk_bf16_f32 v51, v58, v59
	global_store_dwordx4 v[64:65], v[48:51], off
	s_nop 1
	v_cvt_pk_bf16_f32 v48, v52, v53
	v_cvt_pk_bf16_f32 v49, v54, v55
	v_cvt_pk_bf16_f32 v50, v66, v67
	v_cvt_pk_bf16_f32 v51, v68, v69
	global_store_dwordx4 v[64:65], v[48:51], off offset:64
	s_nop 0
	s_nop 0
	v_fmamk_f32 v48, v240, 0x3a800000, v174
	v_mul_f32_e32 v49, 0x4b800000, v48
	v_cmp_gt_f32_e32 vcc, s54, v48
	s_nop 1
	v_cndmask_b32_e32 v48, v48, v49, vcc
	v_rsq_f32_e32 v50, v48
	v_add_u32_e32 v48, 0x90, v164
; __device__ __forceinline__ unsigned pk2(float lo, float hi) { return pg8::cvt_pk_bf16(lo, hi); }
;     __device__ __forceinline__ void operator()(const f32x4 (&acc)[2][2][4][2], const pg8::Unit& u, int wr, int wc, int fr, int fq) const {
;     ...
;                 for (int m = 0; m < 4; ++m) {
;                     const int row = row0 + ai * 128 + m * 16;
;                     const float rs = rsqrtf(sumsq[row] * (1.f / 1024.f) + EPS);
;                     f32x4 v[2][2]; float ss = 0.f;
; #pragma unroll
;                     for (int bj = 0; bj < 2; ++bj)
; #pragma unroll
;                         for (int n = 0; n < 2; ++n) { v[bj][n] = acc[ai][bj][m][n] * rs; ss += (v[bj][n][0] * v[bj][n][0] + v[bj][n][1] * v[bj][n][1]) + (v[bj][n][2] * v[bj][n][2] + v[bj][n][3] * v[bj][n][3]); }
;                     ss += __shfl_xor(ss, 16); ss += __shfl_xor(ss, 32);
;                     const float r = rsqrtf(ss * (1.f / 64.f) + EPS) * sc;
; #pragma unroll
;                     for (int bj = 0; bj < 2; ++bj) {
;                         const f32x4 a = v[bj][0] * wv[bj][0] * r, b = v[bj][1] * wv[bj][1] * r;
;                         u32x4 o; o.x = pk2(a[0], a[1]); o.y = pk2(a[2], a[3]); o.z = pk2(b[0], b[1]); o.w = pk2(b[2], b[3]);
;                         *(u32x4*)(P + (size_t)row * PW + u.pn * 256 + 64 * wc + 32 * bj + 8 * fq) = o;
;                     }
	v_mad_i64_i32 v[48:49], s[2:3], v48, s55, v[168:169]
	v_mul_f32_e32 v51, 0x45800000, v50
	v_cndmask_b32_e32 v50, v50, v51, vcc
	v_mul_f32_e32 v44, v44, v50
	v_mul_f32_e32 v45, v45, v50
	v_mul_f32_e32 v46, v46, v50
	v_mul_f32_e32 v47, v47, v50
	v_mul_f32_e32 v40, v40, v50
	v_mul_f32_e32 v41, v41, v50
	v_mul_f32_e32 v42, v42, v50
	v_mul_f32_e32 v43, v43, v50
	v_mul_f32_e32 v38, v38, v50
	v_mul_f32_e32 v39, v39, v50
	v_mul_f32_e32 v36, v36, v50
	v_mul_f32_e32 v37, v37, v50
	v_mul_f32_e32 v34, v34, v50
	v_mul_f32_e32 v35, v35, v50
	v_mul_f32_e32 v32, v32, v50
	v_mul_f32_e32 v33, v33, v50
	v_mul_f32_e32 v50, v46, v46
	v_mul_f32_e32 v51, v47, v47
	v_mul_f32_e32 v52, v44, v44
	v_mul_f32_e32 v53, v45, v45
	v_mul_f32_e32 v54, v42, v42
	v_mul_f32_e32 v55, v43, v43
	v_mul_f32_e32 v56, v40, v40
	v_mul_f32_e32 v57, v41, v41
	v_pk_mov_b32 v[62:63], v[52:53], v[50:51] op_sel:[1,0]
	v_mov_b32_e32 v53, v51
	v_pk_mov_b32 v[50:51], v[56:57], v[54:55] op_sel:[1,0]
	v_mov_b32_e32 v57, v55
	v_mul_f32_e32 v58, v36, v36
	v_mul_f32_e32 v60, v38, v38
	v_add_f32_e32 v52, v62, v52
	v_add_f32_e32 v53, v63, v53
	v_add_f32_e32 v50, v50, v56
	v_add_f32_e32 v51, v51, v57
	v_fma_f32 v54, v36, v36, v58
	v_fma_f32 v55, v37, v37, v58
	v_fma_f32 v58, v38, v38, v60
	v_fma_f32 v59, v39, v39, v60
	v_add_f32_e32 v53, v52, v53
	v_add_f32_e32 v52, v52, v52
	v_add_f32_e32 v51, v50, v51
	v_add_f32_e32 v50, v50, v50
	v_mul_f32_e32 v54, v32, v32
	v_mul_f32_e32 v58, v33, v33
	v_mul_f32_e32 v52, v34, v34
	v_mul_f32_e32 v50, v35, v35
	v_add_f32_e32 v54, v54, v58
	v_add_f32_e32 v55, v55, v59
	v_add_f32_e32 v50, v52, v50
	v_add_f32_e32 v51, v53, v51
	v_lshl_add_u64 v[48:49], v[48:49], 0, s[0:1]
	v_add_f32_e32 v50, v54, v50
	v_add_f32_e32 v51, v55, v51
	v_lshl_add_u64 v[48:49], v[48:49], 0, s[12:13]
	v_add_f32_e32 v50, v50, v51
	ds_bpermute_b32 v51, v178, v50
	v_mul_f32_e32 v44, v140, v44
	v_mul_f32_e32 v45, v141, v45
	v_mul_f32_e32 v46, v142, v46
	v_mul_f32_e32 v47, v143, v47
	v_mul_f32_e32 v40, v136, v40
	v_mul_f32_e32 v41, v137, v41
	v_mul_f32_e32 v42, v138, v42
	v_mul_f32_e32 v43, v139, v43
	s_waitcnt lgkmcnt(0)
	v_add_f32_e32 v50, v50, v51
	ds_bpermute_b32 v51, v177, v50
	v_mul_f32_e32 v36, v132, v36
	v_mul_f32_e32 v37, v133, v37
	v_mul_f32_e32 v38, v134, v38
	v_mul_f32_e32 v39, v135, v39
	v_mul_f32_e32 v32, v128, v32
	v_mul_f32_e32 v33, v129, v33
	v_mul_f32_e32 v34, v130, v34
	v_mul_f32_e32 v35, v131, v35
	s_waitcnt lgkmcnt(0)
	v_add_f32_e32 v50, v50, v51
	v_fmamk_f32 v50, v50, 0x3c800000, v174
	v_mul_f32_e32 v51, 0x4b800000, v50
	v_cmp_gt_f32_e32 vcc, s54, v50
	v_lshl_add_u64 v[48:49], v[48:49], 0, v[152:153]
	s_nop 0
	v_cndmask_b32_e32 v50, v50, v51, vcc
	v_rsq_f32_e32 v50, v50
	s_nop 0
	v_mul_f32_e32 v51, 0x45800000, v50
	v_cndmask_b32_e32 v50, v50, v51, vcc
	v_mul_f32_e32 v50, v165, v50
	v_mul_f32_e32 v46, v46, v50
	v_mul_f32_e32 v47, v47, v50
	v_mul_f32_e32 v44, v44, v50
	v_mul_f32_e32 v45, v45, v50
	v_mul_f32_e32 v42, v42, v50
	v_mul_f32_e32 v43, v43, v50
	v_mul_f32_e32 v40, v40, v50
	v_mul_f32_e32 v41, v41, v50
	v_mul_f32_e32 v38, v38, v50
	v_mul_f32_e32 v39, v39, v50
	v_mul_f32_e32 v36, v36, v50
	v_mul_f32_e32 v37, v37, v50
	v_mul_f32_e32 v52, v34, v50
	v_mul_f32_e32 v53, v35, v50
	v_mul_f32_e32 v51, v33, v50
	v_mul_f32_e32 v50, v32, v50
	v_cvt_pk_bf16_f32 v32, v44, v45
	v_cvt_pk_bf16_f32 v33, v46, v47
	v_cvt_pk_bf16_f32 v34, v40, v41
	v_cvt_pk_bf16_f32 v35, v42, v43
	global_store_dwordx4 v[48:49], v[32:35], off
	s_nop 1
	v_cvt_pk_bf16_f32 v32, v36, v37
	v_cvt_pk_bf16_f32 v33, v38, v39
	v_cvt_pk_bf16_f32 v34, v50, v51
	v_cvt_pk_bf16_f32 v35, v52, v53
	global_store_dwordx4 v[48:49], v[32:35], off offset:64
	s_nop 0
	s_nop 0
	v_fmamk_f32 v32, v241, 0x3a800000, v174
	v_mul_f32_e32 v33, 0x4b800000, v32
	v_cmp_gt_f32_e32 vcc, s54, v32
	s_nop 1
	v_cndmask_b32_e32 v32, v32, v33, vcc
	v_rsq_f32_e32 v34, v32
	v_add_u32_e32 v32, 0xa0, v164
	v_mad_i64_i32 v[32:33], s[2:3], v32, s55, v[168:169]
	v_mul_f32_e32 v35, 0x45800000, v34
	v_cndmask_b32_e32 v34, v34, v35, vcc
	v_mul_f32_e32 v28, v28, v34
	v_mul_f32_e32 v29, v29, v34
	v_mul_f32_e32 v30, v30, v34
	v_mul_f32_e32 v31, v31, v34
	v_mul_f32_e32 v24, v24, v34
	v_mul_f32_e32 v25, v25, v34
	v_mul_f32_e32 v26, v26, v34
	v_mul_f32_e32 v27, v27, v34
	v_mul_f32_e32 v22, v22, v34
	v_mul_f32_e32 v23, v23, v34
	v_mul_f32_e32 v20, v20, v34
	v_mul_f32_e32 v21, v21, v34
	v_mul_f32_e32 v18, v18, v34
	v_mul_f32_e32 v19, v19, v34
	v_mul_f32_e32 v16, v16, v34
	v_mul_f32_e32 v17, v17, v34
	v_mul_f32_e32 v34, v30, v30
	v_mul_f32_e32 v35, v31, v31
	v_mul_f32_e32 v36, v28, v28
	v_mul_f32_e32 v37, v29, v29
	v_mul_f32_e32 v38, v26, v26
	v_mul_f32_e32 v39, v27, v27
	v_mul_f32_e32 v40, v24, v24
	v_mul_f32_e32 v41, v25, v25
	v_pk_mov_b32 v[46:47], v[36:37], v[34:35] op_sel:[1,0]
	v_mov_b32_e32 v37, v35
	v_pk_mov_b32 v[34:35], v[40:41], v[38:39] op_sel:[1,0]
	v_mov_b32_e32 v41, v39
	v_mul_f32_e32 v42, v20, v20
	v_mul_f32_e32 v44, v22, v22
	v_add_f32_e32 v36, v46, v36
	v_add_f32_e32 v37, v47, v37
	v_add_f32_e32 v34, v34, v40
	v_add_f32_e32 v35, v35, v41
	v_fma_f32 v38, v20, v20, v42
	v_fma_f32 v39, v21, v21, v42
	v_fma_f32 v42, v22, v22, v44
	v_fma_f32 v43, v23, v23, v44
	v_add_f32_e32 v37, v36, v37
	v_add_f32_e32 v36, v36, v36
	v_add_f32_e32 v35, v34, v35
	v_add_f32_e32 v34, v34, v34
	v_mul_f32_e32 v38, v16, v16
	v_mul_f32_e32 v42, v17, v17
	v_mul_f32_e32 v36, v18, v18
	v_mul_f32_e32 v34, v19, v19
	v_add_f32_e32 v38, v38, v42
	v_add_f32_e32 v39, v39, v43
	v_add_f32_e32 v34, v36, v34
	v_add_f32_e32 v35, v37, v35
	v_lshl_add_u64 v[32:33], v[32:33], 0, s[0:1]
	v_add_f32_e32 v34, v38, v34
	v_add_f32_e32 v35, v39, v35
	v_lshl_add_u64 v[32:33], v[32:33], 0, s[12:13]
	v_add_f32_e32 v34, v34, v35
	ds_bpermute_b32 v35, v178, v34
	v_mul_f32_e32 v28, v140, v28
	v_mul_f32_e32 v29, v141, v29
	v_mul_f32_e32 v30, v142, v30
	v_mul_f32_e32 v31, v143, v31
	v_mul_f32_e32 v24, v136, v24
	v_mul_f32_e32 v25, v137, v25
	v_mul_f32_e32 v26, v138, v26
	v_mul_f32_e32 v27, v139, v27
	s_waitcnt lgkmcnt(0)
; __device__ __forceinline__ unsigned pk2(float lo, float hi) { return pg8::cvt_pk_bf16(lo, hi); }
;     __device__ __forceinline__ void operator()(const f32x4 (&acc)[2][2][4][2], const pg8::Unit& u, int wr, int wc, int fr, int fq) const {
;     ...
;                 for (int m = 0; m < 4; ++m) {
;                     const int row = row0 + ai * 128 + m * 16;
;                     const float rs = rsqrtf(sumsq[row] * (1.f / 1024.f) + EPS);
;                     f32x4 v[2][2]; float ss = 0.f;
; #pragma unroll
;                     for (int bj = 0; bj < 2; ++bj)
; #pragma unroll
;                         for (int n = 0; n < 2; ++n) { v[bj][n] = acc[ai][bj][m][n] * rs; ss += (v[bj][n][0] * v[bj][n][0] + v[bj][n][1] * v[bj][n][1]) + (v[bj][n][2] * v[bj][n][2] + v[bj][n][3] * v[bj][n][3]); }
;                     ss += __shfl_xor(ss, 16); ss += __shfl_xor(ss, 32);
;                     const float r = rsqrtf(ss * (1.f / 64.f) + EPS) * sc;
; #pragma unroll
;                     for (int bj = 0; bj < 2; ++bj) {
;                         const f32x4 a = v[bj][0] * wv[bj][0] * r, b = v[bj][1] * wv[bj][1] * r;
;                         u32x4 o; o.x = pk2(a[0], a[1]); o.y = pk2(a[2], a[3]); o.z = pk2(b[0], b[1]); o.w = pk2(b[2], b[3]);
;                         *(u32x4*)(P + (size_t)row * PW + u.pn * 256 + 64 * wc + 32 * bj + 8 * fq) = o;
;                     }
	v_add_f32_e32 v34, v34, v35
	ds_bpermute_b32 v35, v177, v34
	v_mul_f32_e32 v20, v132, v20
	v_mul_f32_e32 v21, v133, v21
	v_mul_f32_e32 v22, v134, v22
	v_mul_f32_e32 v23, v135, v23
	v_mul_f32_e32 v16, v128, v16
	v_mul_f32_e32 v17, v129, v17
	v_mul_f32_e32 v18, v130, v18
	v_mul_f32_e32 v19, v131, v19
	s_waitcnt lgkmcnt(0)
	v_add_f32_e32 v34, v34, v35
	v_fmamk_f32 v34, v34, 0x3c800000, v174
	v_mul_f32_e32 v35, 0x4b800000, v34
	v_cmp_gt_f32_e32 vcc, s54, v34
	v_lshl_add_u64 v[32:33], v[32:33], 0, v[152:153]
	s_nop 0
	v_cndmask_b32_e32 v34, v34, v35, vcc
	v_rsq_f32_e32 v34, v34
	s_nop 0
	v_mul_f32_e32 v35, 0x45800000, v34
	v_cndmask_b32_e32 v34, v34, v35, vcc
	v_mul_f32_e32 v34, v165, v34
	v_mul_f32_e32 v30, v30, v34
	v_mul_f32_e32 v31, v31, v34
	v_mul_f32_e32 v28, v28, v34
	v_mul_f32_e32 v29, v29, v34
	v_mul_f32_e32 v26, v26, v34
	v_mul_f32_e32 v27, v27, v34
	v_mul_f32_e32 v24, v24, v34
	v_mul_f32_e32 v25, v25, v34
	v_mul_f32_e32 v22, v22, v34
	v_mul_f32_e32 v23, v23, v34
	v_mul_f32_e32 v20, v20, v34
	v_mul_f32_e32 v21, v21, v34
	v_mul_f32_e32 v36, v18, v34
	v_mul_f32_e32 v37, v19, v34
	v_mul_f32_e32 v35, v17, v34
	v_mul_f32_e32 v34, v16, v34
	v_cvt_pk_bf16_f32 v16, v28, v29
	v_cvt_pk_bf16_f32 v17, v30, v31
	v_cvt_pk_bf16_f32 v18, v24, v25
	v_cvt_pk_bf16_f32 v19, v26, v27
	global_store_dwordx4 v[32:33], v[16:19], off
	s_nop 1
	v_cvt_pk_bf16_f32 v16, v20, v21
	v_cvt_pk_bf16_f32 v17, v22, v23
	v_cvt_pk_bf16_f32 v18, v34, v35
	v_cvt_pk_bf16_f32 v19, v36, v37
	global_store_dwordx4 v[32:33], v[16:19], off offset:64
	s_nop 0
	s_nop 0
	v_fmamk_f32 v16, v242, 0x3a800000, v174
	v_mul_f32_e32 v17, 0x4b800000, v16
	v_cmp_gt_f32_e32 vcc, s54, v16
	s_nop 1
	v_cndmask_b32_e32 v16, v16, v17, vcc
	v_rsq_f32_e32 v18, v16
	v_add_u32_e32 v16, 0xb0, v164
	v_mad_i64_i32 v[16:17], s[2:3], v16, s55, v[168:169]
	v_mul_f32_e32 v19, 0x45800000, v18
	v_cndmask_b32_e32 v18, v18, v19, vcc
	v_mul_f32_e32 v12, v12, v18
	v_mul_f32_e32 v13, v13, v18
	v_mul_f32_e32 v14, v14, v18
	v_mul_f32_e32 v15, v15, v18
	v_mul_f32_e32 v8, v8, v18
	v_mul_f32_e32 v9, v9, v18
	v_mul_f32_e32 v10, v10, v18
	v_mul_f32_e32 v11, v11, v18
	v_mul_f32_e32 v6, v6, v18
	v_mul_f32_e32 v7, v7, v18
	v_mul_f32_e32 v4, v4, v18
	v_mul_f32_e32 v5, v5, v18
	v_mul_f32_e32 v2, v2, v18
	v_mul_f32_e32 v3, v3, v18
	v_mul_f32_e32 v0, v0, v18
	v_mul_f32_e32 v1, v1, v18
	v_mul_f32_e32 v18, v14, v14
	v_mul_f32_e32 v19, v15, v15
	v_mul_f32_e32 v20, v12, v12
	v_mul_f32_e32 v21, v13, v13
	v_mul_f32_e32 v22, v10, v10
	v_mul_f32_e32 v23, v11, v11
	v_mul_f32_e32 v24, v8, v8
	v_mul_f32_e32 v25, v9, v9
	v_pk_mov_b32 v[30:31], v[20:21], v[18:19] op_sel:[1,0]
	v_mov_b32_e32 v21, v19
	v_pk_mov_b32 v[18:19], v[24:25], v[22:23] op_sel:[1,0]
	v_mov_b32_e32 v25, v23
	v_mul_f32_e32 v26, v4, v4
	v_mul_f32_e32 v28, v6, v6
	v_add_f32_e32 v20, v30, v20
	v_add_f32_e32 v21, v31, v21
	v_add_f32_e32 v18, v18, v24
	v_add_f32_e32 v19, v19, v25
	v_fma_f32 v22, v4, v4, v26
	v_fma_f32 v23, v5, v5, v26
	v_fma_f32 v26, v6, v6, v28
	v_fma_f32 v27, v7, v7, v28
	v_add_f32_e32 v21, v20, v21
	v_add_f32_e32 v20, v20, v20
	v_add_f32_e32 v19, v18, v19
	v_add_f32_e32 v18, v18, v18
	v_mul_f32_e32 v22, v0, v0
	v_mul_f32_e32 v26, v1, v1
	v_mul_f32_e32 v20, v2, v2
	v_mul_f32_e32 v18, v3, v3
	v_add_f32_e32 v22, v22, v26
	v_add_f32_e32 v23, v23, v27
	v_add_f32_e32 v18, v20, v18
	v_add_f32_e32 v19, v21, v19
	v_lshl_add_u64 v[16:17], v[16:17], 0, s[0:1]
	v_add_f32_e32 v18, v22, v18
	v_add_f32_e32 v19, v23, v19
	v_lshl_add_u64 v[16:17], v[16:17], 0, s[12:13]
	v_add_f32_e32 v18, v18, v19
	ds_bpermute_b32 v19, v178, v18
	v_mul_f32_e32 v12, v140, v12
	v_mul_f32_e32 v13, v141, v13
	v_mul_f32_e32 v14, v142, v14
	v_mul_f32_e32 v15, v143, v15
	v_mul_f32_e32 v8, v136, v8
	v_mul_f32_e32 v9, v137, v9
	v_mul_f32_e32 v10, v138, v10
	v_mul_f32_e32 v11, v139, v11
	s_waitcnt lgkmcnt(0)
	v_add_f32_e32 v18, v18, v19
	ds_bpermute_b32 v19, v177, v18
	v_mul_f32_e32 v4, v132, v4
	v_mul_f32_e32 v5, v133, v5
	v_mul_f32_e32 v6, v134, v6
	v_mul_f32_e32 v7, v135, v7
	v_mul_f32_e32 v0, v128, v0
	v_mul_f32_e32 v1, v129, v1
	v_mul_f32_e32 v2, v130, v2
	v_mul_f32_e32 v3, v131, v3
	s_waitcnt lgkmcnt(0)
	v_add_f32_e32 v18, v18, v19
	v_fmamk_f32 v18, v18, 0x3c800000, v174
	v_mul_f32_e32 v19, 0x4b800000, v18
	v_cmp_gt_f32_e32 vcc, s54, v18
	v_lshl_add_u64 v[16:17], v[16:17], 0, v[152:153]
	s_nop 0
	v_cndmask_b32_e32 v18, v18, v19, vcc
	v_rsq_f32_e32 v18, v18
	s_nop 0
	v_mul_f32_e32 v19, 0x45800000, v18
	v_cndmask_b32_e32 v18, v18, v19, vcc
	v_mul_f32_e32 v18, v165, v18
	v_mul_f32_e32 v14, v14, v18
	v_mul_f32_e32 v15, v15, v18
	v_mul_f32_e32 v12, v12, v18
	v_mul_f32_e32 v13, v13, v18
	v_mul_f32_e32 v10, v10, v18
	v_mul_f32_e32 v11, v11, v18
	v_mul_f32_e32 v8, v8, v18
	v_mul_f32_e32 v9, v9, v18
	v_mul_f32_e32 v6, v6, v18
	v_mul_f32_e32 v7, v7, v18
	v_mul_f32_e32 v4, v4, v18
	v_mul_f32_e32 v5, v5, v18
	v_mul_f32_e32 v20, v2, v18
	v_mul_f32_e32 v21, v3, v18
	v_mul_f32_e32 v19, v1, v18
	v_mul_f32_e32 v18, v0, v18
	v_cvt_pk_bf16_f32 v0, v12, v13
	v_cvt_pk_bf16_f32 v1, v14, v15
	v_cvt_pk_bf16_f32 v2, v8, v9
	v_cvt_pk_bf16_f32 v3, v10, v11
	global_store_dwordx4 v[16:17], v[0:3], off
	s_nop 1
	v_cvt_pk_bf16_f32 v0, v4, v5
	v_cvt_pk_bf16_f32 v1, v6, v7
	v_cvt_pk_bf16_f32 v2, v18, v19
	v_cvt_pk_bf16_f32 v3, v20, v21
	global_store_dwordx4 v[16:17], v[0:3], off offset:64
	s_andn2_b64 vcc, exec, s[6:7]
	s_mov_b64 s[0:1], -1
	s_cbranch_vccnz .LBB0_370
